# work-item dequeue: removed the vmcnt(0) before the fetch-add (it only waited on the previous item's stores; the wait after the atomic covers everything)
# baseline (speedup 1.0000x reference)
.LBB0_83:
	s_waitcnt lgkmcnt(0)
	s_barrier
	s_and_saveexec_b64 s[4:5], s[84:85]
	s_cbranch_execz .LBB0_85
	v_readlane_b32 s6, v255, 0
	v_readlane_b32 s7, v255, 1
	s_nop 1
	v_mov_b64_e32 v[0:1], s[6:7]
	flat_atomic_add v0, v[0:1], v154 offset:3328 sc0
	v_mov_b32_e32 v1, s86
	s_waitcnt vmcnt(0) lgkmcnt(0)
	ds_write_b32 v1, v0

.LBB0_152:
	s_waitcnt lgkmcnt(0)
	s_barrier
	s_and_saveexec_b64 s[6:7], s[84:85]
	s_cbranch_execz .LBB0_154
	v_mov_b64_e32 v[0:1], s[10:11]
	flat_atomic_add v0, v[0:1], v154 sc0
	v_mov_b32_e32 v1, s86
	s_waitcnt vmcnt(0) lgkmcnt(0)
	ds_write_b32 v1, v0

.LBB0_193:
	s_waitcnt lgkmcnt(0)
	s_barrier
	s_mov_b64 s[10:11], exec
	v_readlane_b32 s12, v254, 51
	v_readlane_b32 s13, v254, 52
	s_and_b64 s[12:13], s[10:11], s[12:13]
	s_mov_b64 exec, s[12:13]
	s_cbranch_execz .LBB0_195
	v_mov_b64_e32 v[0:1], s[4:5]
	flat_atomic_add v0, v[0:1], v154 offset:1024 sc0
	v_readlane_b32 s0, v254, 50
	s_nop 1
	v_mov_b32_e32 v1, s0
	s_waitcnt vmcnt(0) lgkmcnt(0)
	ds_write_b32 v1, v0

.LBB0_283:
	s_waitcnt lgkmcnt(0)
	s_barrier
	s_and_saveexec_b64 s[10:11], s[84:85]
	s_cbranch_execz .LBB0_285
	v_mov_b64_e32 v[0:1], s[20:21]
	flat_atomic_add v0, v[0:1], v154 offset:768 sc0
	v_mov_b32_e32 v1, s86
	s_waitcnt vmcnt(0) lgkmcnt(0)
	ds_write_b32 v1, v0
